# S5: pass-1 U-tile prefetch 4 steps deep in batches; pass-2 scan b-values preloaded from LDS, skip loads hoisted to step start
# baseline (speedup 1.0000x reference)
.LBB0_1016:
	s_or_b64 exec, exec, s[14:15]
	s_and_b32 s14, s1, 0x2000
	s_and_b32 s15, s16, 0x7f
	s_add_u32 s12, s12, s14
	s_addc_u32 s13, s13, 0
	v_lshl_add_u64 v[34:35], s[12:13], 0, v[42:43]
	v_lshlrev_b64 v[34:35], 12, v[34:35]
	v_lshl_or_b32 v34, s15, 5, v34
	s_waitcnt vmcnt(0) lgkmcnt(0)
	v_pk_mov_b32 v[54:55], v[52:53], v[52:53] op_sel:[1,0]
	v_lshl_add_u64 v[56:57], v[50:51], 0, v[34:35]
	v_mov_b32_e32 v59, v58
	v_mov_b32_e32 v146, 0
	v_mov_b32_e32 v147, 0
	v_mov_b32_e32 v148, 0
	v_mov_b32_e32 v149, 0
	v_mov_b32_e32 v150, 0
	v_mov_b32_e32 v151, 0
	v_mov_b32_e32 v152, 0
	v_mov_b32_e32 v153, 0
	v_mov_b32_e32 v154, 0
	v_mov_b32_e32 v155, 0
	v_mov_b32_e32 v156, 0
	v_mov_b32_e32 v157, 0
	v_mov_b32_e32 v158, 0
	v_mov_b32_e32 v159, 0
	v_mov_b32_e32 v160, 0
	v_mov_b32_e32 v161, 0
	v_mov_b32_e32 v194, 0
	v_mov_b32_e32 v195, 0
	v_mov_b32_e32 v196, 0
	v_mov_b32_e32 v197, 0
	v_mov_b32_e32 v198, 0
	v_mov_b32_e32 v199, 0
	v_mov_b32_e32 v200, 0
	v_mov_b32_e32 v201, 0
	v_mov_b32_e32 v202, 0
	v_mov_b32_e32 v203, 0
	v_mov_b32_e32 v204, 0
	v_mov_b32_e32 v205, 0
	v_mov_b32_e32 v206, 0
	v_mov_b32_e32 v207, 0
	v_mov_b32_e32 v208, 0
	v_mov_b32_e32 v209, 0
	s_mov_b64 s[100:101], 0x10000
	v_mov_b64_e32 v[210:211], v[56:57]
	s_and_saveexec_b64 s[14:15], s[4:5]
	global_load_dwordx4 v[146:149], v[210:211], off
	v_lshl_add_u64 v[210:211], v[210:211], 0, s[100:101]
	global_load_dwordx4 v[150:153], v[210:211], off
	v_lshl_add_u64 v[210:211], v[210:211], 0, s[100:101]
	global_load_dwordx4 v[154:157], v[210:211], off
	v_lshl_add_u64 v[210:211], v[210:211], 0, s[100:101]
	global_load_dwordx4 v[158:161], v[210:211], off
	v_lshl_add_u64 v[210:211], v[210:211], 0, s[100:101]
	global_load_dwordx4 v[194:197], v[210:211], off
	v_lshl_add_u64 v[210:211], v[210:211], 0, s[100:101]
	global_load_dwordx4 v[198:201], v[210:211], off
	v_lshl_add_u64 v[210:211], v[210:211], 0, s[100:101]
	global_load_dwordx4 v[202:205], v[210:211], off
	v_lshl_add_u64 v[210:211], v[210:211], 0, s[100:101]
	global_load_dwordx4 v[206:209], v[210:211], off
	v_lshl_add_u64 v[210:211], v[210:211], 0, s[100:101]
	s_or_b64 exec, exec, s[14:15]
	s_waitcnt vmcnt(4)
	s_branch .LBB0_1018
.LBB0_1017:
	v_mfma_f32_16x16x32_bf16 v[62:65], v[38:41], v[2:5], 0
	v_add_u32_e32 v0, 0x400, v61
	s_mov_b64 s[14:15], 0x10000
	s_add_i32 s11, s11, 16
	v_mfma_f32_16x16x32_bf16 v[66:69], v[38:41], v[6:9], 0
	v_lshl_add_u64 v[56:57], v[56:57], 0, s[14:15]
	s_and_b64 vcc, exec, s[12:13]
	v_mfma_f32_16x16x32_bf16 v[70:73], v[38:41], v[10:13], 0
	v_mfma_f32_16x16x32_bf16 v[74:77], v[38:41], v[14:17], 0
	s_nop 3
	ds_write2_b32 v61, v62, v66 offset1:16
	ds_write2_b32 v61, v63, v67 offset0:132 offset1:148
	ds_write2_b32 v0, v64, v68 offset0:8 offset1:24
	v_mfma_f32_16x16x32_bf16 v[78:81], v[38:41], v[18:21], 0
	ds_write2_b32 v0, v65, v69 offset0:140 offset1:156
	ds_write2_b32 v61, v70, v74 offset0:32 offset1:48
	ds_write2_b32 v61, v71, v75 offset0:164 offset1:180
	v_mfma_f32_16x16x32_bf16 v[62:65], v[38:41], v[22:25], 0
	ds_write2_b32 v0, v72, v76 offset0:40 offset1:56
	ds_write2_b32 v0, v73, v77 offset0:172 offset1:188
	s_nop 5
	ds_write2_b32 v61, v78, v62 offset0:64 offset1:80
	ds_write2_b32 v61, v79, v63 offset0:196 offset1:212
	ds_write2_b32 v0, v80, v64 offset0:72 offset1:88
	ds_write2_b32 v0, v81, v65 offset0:204 offset1:220
	v_mfma_f32_16x16x32_bf16 v[66:69], v[38:41], v[26:29], 0
	v_mfma_f32_16x16x32_bf16 v[38:41], v[38:41], v[30:33], 0
	s_nop 7
	ds_write2_b32 v61, v66, v38 offset0:96 offset1:112
	ds_write2_b32 v61, v67, v39 offset0:228 offset1:244
	ds_write2_b32 v0, v68, v40 offset0:104 offset1:120
	ds_write2_b32 v0, v69, v41 offset0:236 offset1:252
	ds_read2st64_b32 v[38:39], v60 offset1:1
	v_pk_mul_f32 v[40:41], v[52:53], v[58:59]
	s_nop 0
	v_sub_f32_e32 v0, v40, v41
	v_pk_mul_f32 v[40:41], v[54:55], v[58:59]
	s_waitcnt lgkmcnt(0)
	v_add_f32_e32 v0, v0, v38
	v_add_f32_e32 v38, v40, v41
	ds_read2_b32 v[40:41], v60 offset0:132 offset1:196
	v_add_f32_e32 v38, v38, v39
	v_add_u32_e32 v39, 32, v60
	ds_read2st64_b32 v[58:59], v39 offset0:4 offset1:5
	v_pk_mul_f32 v[38:39], v[54:55], v[38:39] op_sel_hi:[1,0]
	s_nop 0
	v_pk_fma_f32 v[62:63], v[52:53], v[0:1], v[38:39] neg_lo:[0,0,1] neg_hi:[0,0,1]
	v_pk_fma_f32 v[38:39], v[52:53], v[0:1], v[38:39] op_sel_hi:[1,0,1]
	s_nop 0
	v_mov_b32_e32 v63, v39
	s_waitcnt lgkmcnt(0)
	v_pk_add_f32 v[38:39], v[40:41], v[62:63]
	s_nop 0
	v_pk_mul_f32 v[40:41], v[52:53], v[38:39]
	v_pk_mul_f32 v[38:39], v[52:53], v[38:39] op_sel:[0,1] op_sel_hi:[1,0]
	v_sub_f32_e32 v0, v40, v41
	v_add_f32_e32 v38, v38, v39
	v_add_u32_e32 v39, 48, v60
	ds_read2st64_b32 v[40:41], v39 offset0:6 offset1:7
	v_add_f32_e32 v38, v59, v38
	v_add_u32_e32 v39, 64, v60
	v_add_f32_e32 v0, v58, v0
	ds_read2st64_b32 v[58:59], v39 offset0:8 offset1:9
	v_pk_mul_f32 v[38:39], v[54:55], v[38:39] op_sel_hi:[1,0]
	s_nop 0
	v_pk_fma_f32 v[62:63], v[52:53], v[0:1], v[38:39] neg_lo:[0,0,1] neg_hi:[0,0,1]
	v_pk_fma_f32 v[38:39], v[52:53], v[0:1], v[38:39] op_sel_hi:[1,0,1]
	s_nop 0
	v_mov_b32_e32 v63, v39
	s_waitcnt lgkmcnt(0)
	v_pk_add_f32 v[38:39], v[40:41], v[62:63]
	s_nop 0
	v_pk_mul_f32 v[40:41], v[52:53], v[38:39]
	v_pk_mul_f32 v[38:39], v[52:53], v[38:39] op_sel:[0,1] op_sel_hi:[1,0]
	v_sub_f32_e32 v0, v40, v41
	v_add_f32_e32 v38, v38, v39
	v_add_u32_e32 v39, 0x50, v60
	ds_read2st64_b32 v[40:41], v39 offset0:10 offset1:11
	v_add_f32_e32 v38, v59, v38
	v_add_u32_e32 v39, 0x60, v60
	v_add_f32_e32 v0, v58, v0
	ds_read2st64_b32 v[58:59], v39 offset0:12 offset1:13
	v_pk_mul_f32 v[38:39], v[54:55], v[38:39] op_sel_hi:[1,0]
	s_nop 0
	v_pk_fma_f32 v[62:63], v[52:53], v[0:1], v[38:39] neg_lo:[0,0,1] neg_hi:[0,0,1]
	v_pk_fma_f32 v[38:39], v[52:53], v[0:1], v[38:39] op_sel_hi:[1,0,1]
	s_nop 0
	v_mov_b32_e32 v63, v39
	s_waitcnt lgkmcnt(0)
	v_pk_add_f32 v[38:39], v[40:41], v[62:63]
	s_nop 0
	v_pk_mul_f32 v[40:41], v[52:53], v[38:39]
	v_pk_mul_f32 v[38:39], v[52:53], v[38:39] op_sel:[0,1] op_sel_hi:[1,0]
	v_sub_f32_e32 v0, v40, v41
	v_add_f32_e32 v38, v38, v39
	v_add_u32_e32 v39, 0x70, v60
	ds_read2st64_b32 v[40:41], v39 offset0:14 offset1:15
	v_add_f32_e32 v38, v59, v38
	v_add_u32_e32 v39, 0x80, v60
	v_add_f32_e32 v0, v58, v0
	ds_read2st64_b32 v[58:59], v39 offset0:16 offset1:17
	v_pk_mul_f32 v[38:39], v[54:55], v[38:39] op_sel_hi:[1,0]
	s_nop 0
	v_pk_fma_f32 v[62:63], v[52:53], v[0:1], v[38:39] neg_lo:[0,0,1] neg_hi:[0,0,1]
	v_pk_fma_f32 v[38:39], v[52:53], v[0:1], v[38:39] op_sel_hi:[1,0,1]
	s_nop 0
	v_mov_b32_e32 v63, v39
	s_waitcnt lgkmcnt(0)
	v_pk_add_f32 v[38:39], v[40:41], v[62:63]
	s_nop 0
	v_pk_mul_f32 v[40:41], v[52:53], v[38:39]
	v_pk_mul_f32 v[38:39], v[52:53], v[38:39] op_sel:[0,1] op_sel_hi:[1,0]
	v_sub_f32_e32 v0, v40, v41
	v_add_f32_e32 v38, v38, v39
	v_add_u32_e32 v39, 0x90, v60
	ds_read2st64_b32 v[40:41], v39 offset0:18 offset1:19
	v_add_f32_e32 v38, v59, v38
	v_add_u32_e32 v39, 0xa0, v60
	v_add_f32_e32 v0, v58, v0
	ds_read2st64_b32 v[58:59], v39 offset0:20 offset1:21
	v_pk_mul_f32 v[38:39], v[54:55], v[38:39] op_sel_hi:[1,0]
	s_nop 0
	v_pk_fma_f32 v[62:63], v[52:53], v[0:1], v[38:39] neg_lo:[0,0,1] neg_hi:[0,0,1]
	v_pk_fma_f32 v[38:39], v[52:53], v[0:1], v[38:39] op_sel_hi:[1,0,1]
	s_nop 0
	v_mov_b32_e32 v63, v39
	s_waitcnt lgkmcnt(0)
	v_pk_add_f32 v[38:39], v[40:41], v[62:63]
	s_nop 0
	v_pk_mul_f32 v[40:41], v[52:53], v[38:39]
	v_pk_mul_f32 v[38:39], v[52:53], v[38:39] op_sel:[0,1] op_sel_hi:[1,0]
	v_sub_f32_e32 v0, v40, v41
	v_add_f32_e32 v38, v38, v39
	v_add_u32_e32 v39, 0xb0, v60
	ds_read2st64_b32 v[40:41], v39 offset0:22 offset1:23
	v_add_f32_e32 v38, v59, v38
	v_add_u32_e32 v39, 0xc0, v60
	v_add_f32_e32 v0, v58, v0
	ds_read2st64_b32 v[58:59], v39 offset0:24 offset1:25
	v_pk_mul_f32 v[38:39], v[54:55], v[38:39] op_sel_hi:[1,0]
	s_nop 0
	v_pk_fma_f32 v[62:63], v[52:53], v[0:1], v[38:39] neg_lo:[0,0,1] neg_hi:[0,0,1]
	v_pk_fma_f32 v[38:39], v[52:53], v[0:1], v[38:39] op_sel_hi:[1,0,1]
	s_nop 0
	v_mov_b32_e32 v63, v39
	s_waitcnt lgkmcnt(0)
	v_pk_add_f32 v[38:39], v[40:41], v[62:63]
	s_nop 0
	v_pk_mul_f32 v[40:41], v[52:53], v[38:39]
	v_pk_mul_f32 v[38:39], v[52:53], v[38:39] op_sel:[0,1] op_sel_hi:[1,0]
	v_sub_f32_e32 v0, v40, v41
	v_add_f32_e32 v38, v38, v39
	v_add_u32_e32 v39, 0xd0, v60
	ds_read2st64_b32 v[40:41], v39 offset0:26 offset1:27
	v_add_f32_e32 v38, v59, v38
	v_add_u32_e32 v39, 0xe0, v60
	v_add_f32_e32 v0, v58, v0
	ds_read2st64_b32 v[58:59], v39 offset0:28 offset1:29
	v_pk_mul_f32 v[38:39], v[54:55], v[38:39] op_sel_hi:[1,0]
	s_nop 0
	v_pk_fma_f32 v[62:63], v[52:53], v[0:1], v[38:39] neg_lo:[0,0,1] neg_hi:[0,0,1]
	v_pk_fma_f32 v[38:39], v[52:53], v[0:1], v[38:39] op_sel_hi:[1,0,1]
	s_nop 0
	v_mov_b32_e32 v63, v39
	s_waitcnt lgkmcnt(0)
	v_pk_add_f32 v[38:39], v[40:41], v[62:63]
	s_nop 0
	v_pk_mul_f32 v[40:41], v[52:53], v[38:39]
	v_pk_mul_f32 v[38:39], v[52:53], v[38:39] op_sel:[0,1] op_sel_hi:[1,0]
	v_sub_f32_e32 v0, v40, v41
	v_add_f32_e32 v38, v38, v39
	v_add_u32_e32 v39, 0xf0, v60
	ds_read2st64_b32 v[40:41], v39 offset0:30 offset1:31
	v_add_f32_e32 v38, v59, v38
	v_add_f32_e32 v0, v58, v0
	v_pk_mul_f32 v[38:39], v[54:55], v[38:39] op_sel_hi:[1,0]
	s_nop 0
	v_pk_fma_f32 v[58:59], v[52:53], v[0:1], v[38:39] neg_lo:[0,0,1] neg_hi:[0,0,1]
	v_pk_fma_f32 v[38:39], v[52:53], v[0:1], v[38:39] op_sel_hi:[1,0,1]
	s_nop 0
	v_mov_b32_e32 v59, v39
	s_waitcnt lgkmcnt(0)
	v_pk_add_f32 v[58:59], v[40:41], v[58:59]
	v_mov_b32_e32 v38, v146
	v_mov_b32_e32 v39, v147
	v_mov_b32_e32 v40, v148
	v_mov_b32_e32 v41, v149
	v_mov_b64_e32 v[146:147], v[150:151]
	v_mov_b64_e32 v[148:149], v[152:153]
	v_mov_b64_e32 v[150:151], v[154:155]
	v_mov_b64_e32 v[152:153], v[156:157]
	v_mov_b64_e32 v[154:155], v[158:159]
	v_mov_b64_e32 v[156:157], v[160:161]
	s_and_b32 s14, s11, 63
	s_cmp_lg_u32 s14, 0
	s_cbranch_scc1 .Ls5a_norefill
	s_waitcnt vmcnt(0)
	v_mov_b64_e32 v[146:147], v[194:195]
	v_mov_b64_e32 v[148:149], v[196:197]
	v_mov_b64_e32 v[150:151], v[198:199]
	v_mov_b64_e32 v[152:153], v[200:201]
	v_mov_b64_e32 v[154:155], v[202:203]
	v_mov_b64_e32 v[156:157], v[204:205]
	v_mov_b64_e32 v[158:159], v[206:207]
	v_mov_b64_e32 v[160:161], v[208:209]
	s_and_saveexec_b64 s[14:15], s[4:5]
	global_load_dwordx4 v[194:197], v[210:211], off
	v_lshl_add_u64 v[210:211], v[210:211], 0, s[100:101]
	global_load_dwordx4 v[198:201], v[210:211], off
	v_lshl_add_u64 v[210:211], v[210:211], 0, s[100:101]
	global_load_dwordx4 v[202:205], v[210:211], off
	v_lshl_add_u64 v[210:211], v[210:211], 0, s[100:101]
	global_load_dwordx4 v[206:209], v[210:211], off
	v_lshl_add_u64 v[210:211], v[210:211], 0, s[100:101]
	s_or_b64 exec, exec, s[14:15]
.Ls5a_norefill:
	s_cbranch_vccnz .LBB0_997
.LBB0_1018:
	s_cmpk_gt_u32 s11, 0x3ef
	s_cselect_b64 s[12:13], -1, 0
	s_branch .LBB0_1017

.LBB0_1090:
	s_or_b64 exec, exec, s[16:17]
	s_mov_b64 s[100:101], 0x2000
	global_load_ushort v102, v[86:87], off
	v_lshl_add_u64 v[106:107], v[86:87], 0, s[100:101]
	global_load_ushort v103, v[106:107], off offset:-4096
	global_load_ushort v104, v[106:107], off
	v_lshl_add_u64 v[106:107], v[106:107], 0, s[100:101]
	global_load_ushort v105, v[106:107], off offset:-4096
	v_mfma_f32_16x16x32_bf16 v[94:97], v[54:57], v[2:5], 0
	v_add_u32_e32 v93, 0x400, v59
	s_mov_b64 s[22:23], 0x10000
	s_mov_b64 s[16:17], 0x8000
	v_mfma_f32_16x16x32_bf16 v[98:101], v[54:57], v[6:9], 0
	s_nop 7
	ds_write2_b32 v59, v94, v98 offset1:16
	ds_write2_b32 v59, v95, v99 offset0:132 offset1:148
	ds_write2_b32 v93, v96, v100 offset0:8 offset1:24
	ds_write2_b32 v93, v97, v101 offset0:140 offset1:156
	v_mfma_f32_16x16x32_bf16 v[94:97], v[54:57], v[10:13], 0
	s_add_i32 s20, s20, 16
	v_lshl_add_u64 v[80:81], v[80:81], 0, s[22:23]
	s_and_b64 vcc, exec, s[14:15]
	v_mfma_f32_16x16x32_bf16 v[98:101], v[54:57], v[14:17], 0
	s_nop 7
	ds_write2_b32 v59, v94, v98 offset0:32 offset1:48
	ds_write2_b32 v59, v95, v99 offset0:164 offset1:180
	ds_write2_b32 v93, v96, v100 offset0:40 offset1:56
	ds_write2_b32 v93, v97, v101 offset0:172 offset1:188
	v_mfma_f32_16x16x32_bf16 v[94:97], v[54:57], v[18:21], 0
	v_mfma_f32_16x16x32_bf16 v[98:101], v[54:57], v[22:25], 0
	s_nop 7
	ds_write2_b32 v59, v94, v98 offset0:64 offset1:80
	ds_write2_b32 v59, v95, v99 offset0:196 offset1:212
	ds_write2_b32 v93, v96, v100 offset0:72 offset1:88
	ds_write2_b32 v93, v97, v101 offset0:204 offset1:220
	v_mfma_f32_16x16x32_bf16 v[94:97], v[54:57], v[26:29], 0
	v_mfma_f32_16x16x32_bf16 v[54:57], v[54:57], v[30:33], 0
	s_nop 7
	ds_write2_b32 v59, v94, v54 offset0:96 offset1:112
	ds_write2_b32 v59, v95, v55 offset0:228 offset1:244
	ds_write2_b32 v93, v96, v56 offset0:104 offset1:120
	ds_write2_b32 v93, v97, v57 offset0:236 offset1:252
	ds_read_b32 v110, v90
	ds_read_b32 v111, v90 offset:256
	ds_read_b32 v112, v90 offset:528
	ds_read_b32 v113, v90 offset:784
	ds_read_b32 v114, v90 offset:1056
	ds_read_b32 v115, v90 offset:1312
	ds_read_b32 v116, v90 offset:1584
	ds_read_b32 v117, v90 offset:1840
	ds_read_b32 v118, v90 offset:2112
	ds_read_b32 v119, v90 offset:2368
	ds_read_b32 v120, v90 offset:2640
	ds_read_b32 v121, v90 offset:2896
	ds_read_b32 v122, v90 offset:3168
	ds_read_b32 v123, v90 offset:3424
	ds_read_b32 v124, v90 offset:3696
	ds_read_b32 v125, v90 offset:3952
	ds_read_b32 v126, v90 offset:4224
	ds_read_b32 v127, v90 offset:4480
	ds_read_b32 v128, v90 offset:4752
	ds_read_b32 v129, v90 offset:5008
	ds_read_b32 v130, v90 offset:5280
	ds_read_b32 v131, v90 offset:5536
	ds_read_b32 v132, v90 offset:5808
	ds_read_b32 v133, v90 offset:6064
	ds_read_b32 v134, v90 offset:6336
	ds_read_b32 v135, v90 offset:6592
	ds_read_b32 v136, v90 offset:6864
	ds_read_b32 v137, v90 offset:7120
	ds_read_b32 v138, v90 offset:7392
	ds_read_b32 v139, v90 offset:7648
	ds_read_b32 v140, v90 offset:7920
	ds_read_b32 v141, v90 offset:8176
	s_waitcnt lgkmcnt(0)
	v_mul_f32_e32 v54, v77, v89
	v_mul_f32_e32 v55, v76, v89
	v_fma_f32 v56, v76, v88, -v54
	v_fmac_f32_e32 v55, v77, v88
	v_add_f32_e32 v56, v56, v110
	v_add_f32_e32 v57, v55, v111
	v_mul_f32_e32 v54, v77, v57
	v_mul_f32_e32 v55, v76, v57
	v_bfe_u32 v142, v56, 16, 1
	v_add3_u32 v142, v56, v142, s97
	ds_write_b16_d16_hi v91, v142 offset:8448
	v_fma_f32 v88, v76, v56, -v54
	v_fmac_f32_e32 v55, v77, v56
	v_bfe_u32 v143, v57, 16, 1
	v_add3_u32 v143, v57, v143, s97
	ds_write_b16_d16_hi v91, v143 offset:8576
	v_add_f32_e32 v88, v88, v112
	v_add_f32_e32 v89, v55, v113
	v_mul_f32_e32 v54, v77, v89
	v_mul_f32_e32 v55, v76, v89
	v_bfe_u32 v142, v88, 16, 1
	v_add3_u32 v142, v88, v142, s97
	ds_write_b16_d16_hi v91, v142 offset:8720
	v_fma_f32 v56, v76, v88, -v54
	v_fmac_f32_e32 v55, v77, v88
	v_bfe_u32 v143, v89, 16, 1
	v_add3_u32 v143, v89, v143, s97
	ds_write_b16_d16_hi v91, v143 offset:8848
	v_add_f32_e32 v56, v56, v114
	v_add_f32_e32 v57, v55, v115
	v_mul_f32_e32 v54, v77, v57
	v_mul_f32_e32 v55, v76, v57
	v_bfe_u32 v142, v56, 16, 1
	v_add3_u32 v142, v56, v142, s97
	ds_write_b16_d16_hi v91, v142 offset:8992
	v_fma_f32 v88, v76, v56, -v54
	v_fmac_f32_e32 v55, v77, v56
	v_bfe_u32 v143, v57, 16, 1
	v_add3_u32 v143, v57, v143, s97
	ds_write_b16_d16_hi v91, v143 offset:9120
	v_add_f32_e32 v88, v88, v116
	v_add_f32_e32 v89, v55, v117
	v_mul_f32_e32 v54, v77, v89
	v_mul_f32_e32 v55, v76, v89
	v_bfe_u32 v142, v88, 16, 1
	v_add3_u32 v142, v88, v142, s97
	ds_write_b16_d16_hi v91, v142 offset:9264
	v_fma_f32 v56, v76, v88, -v54
	v_fmac_f32_e32 v55, v77, v88
	v_bfe_u32 v143, v89, 16, 1
	v_add3_u32 v143, v89, v143, s97
	ds_write_b16_d16_hi v91, v143 offset:9392
	v_add_f32_e32 v56, v56, v118
	v_add_f32_e32 v57, v55, v119
	v_mul_f32_e32 v54, v77, v57
	v_mul_f32_e32 v55, v76, v57
	v_bfe_u32 v142, v56, 16, 1
	v_add3_u32 v142, v56, v142, s97
	ds_write_b16_d16_hi v91, v142 offset:9536
	v_fma_f32 v88, v76, v56, -v54
	v_fmac_f32_e32 v55, v77, v56
	v_bfe_u32 v143, v57, 16, 1
	v_add3_u32 v143, v57, v143, s97
	ds_write_b16_d16_hi v91, v143 offset:9664
	v_add_f32_e32 v88, v88, v120
	v_add_f32_e32 v89, v55, v121
	v_mul_f32_e32 v54, v77, v89
	v_mul_f32_e32 v55, v76, v89
	v_bfe_u32 v142, v88, 16, 1
	v_add3_u32 v142, v88, v142, s97
	ds_write_b16_d16_hi v91, v142 offset:9808
	v_fma_f32 v56, v76, v88, -v54
	v_fmac_f32_e32 v55, v77, v88
	v_bfe_u32 v143, v89, 16, 1
	v_add3_u32 v143, v89, v143, s97
	ds_write_b16_d16_hi v91, v143 offset:9936
	v_add_f32_e32 v56, v56, v122
	v_add_f32_e32 v57, v55, v123
	v_mul_f32_e32 v54, v77, v57
	v_mul_f32_e32 v55, v76, v57
	v_bfe_u32 v142, v56, 16, 1
	v_add3_u32 v142, v56, v142, s97
	ds_write_b16_d16_hi v91, v142 offset:10080
	v_fma_f32 v88, v76, v56, -v54
	v_fmac_f32_e32 v55, v77, v56
	v_bfe_u32 v143, v57, 16, 1
	v_add3_u32 v143, v57, v143, s97
	ds_write_b16_d16_hi v91, v143 offset:10208
	v_add_f32_e32 v88, v88, v124
	v_add_f32_e32 v89, v55, v125
	v_mul_f32_e32 v54, v77, v89
	v_mul_f32_e32 v55, v76, v89
	v_bfe_u32 v142, v88, 16, 1
	v_add3_u32 v142, v88, v142, s97
	ds_write_b16_d16_hi v91, v142 offset:10352
	v_fma_f32 v56, v76, v88, -v54
	v_fmac_f32_e32 v55, v77, v88
	v_bfe_u32 v143, v89, 16, 1
	v_add3_u32 v143, v89, v143, s97
	ds_write_b16_d16_hi v91, v143 offset:10480
	v_add_f32_e32 v56, v56, v126
	v_add_f32_e32 v57, v55, v127
	v_mul_f32_e32 v54, v77, v57
	v_mul_f32_e32 v55, v76, v57
	v_bfe_u32 v142, v56, 16, 1
	v_add3_u32 v142, v56, v142, s97
	ds_write_b16_d16_hi v91, v142 offset:10624
	v_fma_f32 v88, v76, v56, -v54
	v_fmac_f32_e32 v55, v77, v56
	v_bfe_u32 v143, v57, 16, 1
	v_add3_u32 v143, v57, v143, s97
	ds_write_b16_d16_hi v91, v143 offset:10752
	v_add_f32_e32 v88, v88, v128
	v_add_f32_e32 v89, v55, v129
	v_mul_f32_e32 v54, v77, v89
	v_mul_f32_e32 v55, v76, v89
	v_bfe_u32 v142, v88, 16, 1
	v_add3_u32 v142, v88, v142, s97
	ds_write_b16_d16_hi v91, v142 offset:10896
	v_fma_f32 v56, v76, v88, -v54
	v_fmac_f32_e32 v55, v77, v88
	v_bfe_u32 v143, v89, 16, 1
	v_add3_u32 v143, v89, v143, s97
	ds_write_b16_d16_hi v91, v143 offset:11024
	v_add_f32_e32 v56, v56, v130
	v_add_f32_e32 v57, v55, v131
	v_mul_f32_e32 v54, v77, v57
	v_mul_f32_e32 v55, v76, v57
	v_bfe_u32 v142, v56, 16, 1
	v_add3_u32 v142, v56, v142, s97
	ds_write_b16_d16_hi v91, v142 offset:11168
	v_fma_f32 v88, v76, v56, -v54
	v_fmac_f32_e32 v55, v77, v56
	v_bfe_u32 v143, v57, 16, 1
	v_add3_u32 v143, v57, v143, s97
	ds_write_b16_d16_hi v91, v143 offset:11296
	v_add_f32_e32 v88, v88, v132
	v_add_f32_e32 v89, v55, v133
	v_mul_f32_e32 v54, v77, v89
	v_mul_f32_e32 v55, v76, v89
	v_bfe_u32 v142, v88, 16, 1
	v_add3_u32 v142, v88, v142, s97
	ds_write_b16_d16_hi v91, v142 offset:11440
	v_fma_f32 v56, v76, v88, -v54
	v_fmac_f32_e32 v55, v77, v88
	v_bfe_u32 v143, v89, 16, 1
	v_add3_u32 v143, v89, v143, s97
	ds_write_b16_d16_hi v91, v143 offset:11568
	v_add_f32_e32 v56, v56, v134
	v_add_f32_e32 v57, v55, v135
	v_mul_f32_e32 v54, v77, v57
	v_mul_f32_e32 v55, v76, v57
	v_bfe_u32 v142, v56, 16, 1
	v_add3_u32 v142, v56, v142, s97
	ds_write_b16_d16_hi v91, v142 offset:11712
	v_fma_f32 v88, v76, v56, -v54
	v_fmac_f32_e32 v55, v77, v56
	v_bfe_u32 v143, v57, 16, 1
	v_add3_u32 v143, v57, v143, s97
	ds_write_b16_d16_hi v91, v143 offset:11840
	v_add_f32_e32 v88, v88, v136
	v_add_f32_e32 v89, v55, v137
	v_mul_f32_e32 v54, v77, v89
	v_mul_f32_e32 v55, v76, v89
	v_bfe_u32 v142, v88, 16, 1
	v_add3_u32 v142, v88, v142, s97
	ds_write_b16_d16_hi v91, v142 offset:11984
	v_fma_f32 v56, v76, v88, -v54
	v_fmac_f32_e32 v55, v77, v88
	v_bfe_u32 v143, v89, 16, 1
	v_add3_u32 v143, v89, v143, s97
	ds_write_b16_d16_hi v91, v143 offset:12112
	v_add_f32_e32 v56, v56, v138
	v_add_f32_e32 v57, v55, v139
	v_mul_f32_e32 v54, v77, v57
	v_mul_f32_e32 v55, v76, v57
	v_bfe_u32 v142, v56, 16, 1
	v_add3_u32 v142, v56, v142, s97
	ds_write_b16_d16_hi v91, v142 offset:12256
	v_fma_f32 v88, v76, v56, -v54
	v_fmac_f32_e32 v55, v77, v56
	v_bfe_u32 v143, v57, 16, 1
	v_add3_u32 v143, v57, v143, s97
	ds_write_b16_d16_hi v91, v143 offset:12384
	v_add_f32_e32 v88, v88, v140
	v_add_f32_e32 v89, v55, v141
	v_bfe_u32 v142, v88, 16, 1
	v_add3_u32 v142, v88, v142, s97
	ds_write_b16_d16_hi v91, v142 offset:12528
	v_bfe_u32 v143, v89, 16, 1
	v_add3_u32 v143, v89, v143, s97
	ds_write_b16_d16_hi v91, v143 offset:12656
	ds_read_b128 v[54:57], v63 offset:8448
	ds_read_b128 v[94:97], v63 offset:8512
	s_waitcnt lgkmcnt(0)
	v_mfma_f32_16x16x32_bf16 v[54:57], v[54:57], v[34:37], 0
	v_lshl_add_u64 v[86:87], v[86:87], 0, s[22:23]
	s_waitcnt vmcnt(0)
	v_lshlrev_b32_e32 v93, 16, v102
	v_mfma_f32_16x16x32_bf16 v[54:57], v[94:97], v[38:41], v[54:57]
	ds_read_b128 v[94:97], v63 offset:8576
	s_waitcnt lgkmcnt(0)
	v_mfma_f32_16x16x32_bf16 v[54:57], v[94:97], v[42:45], v[54:57]
	ds_read_b128 v[94:97], v63 offset:8640
	s_waitcnt lgkmcnt(0)
	v_mfma_f32_16x16x32_bf16 v[54:57], v[94:97], v[46:49], v[54:57]
	v_lshlrev_b64 v[94:95], 1, v[82:83]
	v_or_b32_e32 v96, 0x1000, v94
	v_mov_b32_e32 v97, v95
	s_nop 4
	v_fma_f32 v54, v92, v93, v54
	v_mul_f32_e32 v93, 0x3d372713, v54
	v_mul_f32_e32 v93, v54, v93
	v_fma_f32 v93, v54, v93, v54
	v_mul_f32_e32 v93, 0x3f4c422a, v93
	v_add_f32_e32 v93, v93, v93
	v_mul_f32_e32 v93, 0x3fb8aa3b, v93
	v_exp_f32_e32 v93, v93
	v_lshl_add_u64 v[98:99], s[6:7], 0, v[96:97]
	v_lshl_add_u64 v[82:83], v[82:83], 0, s[16:17]
	v_add_f32_e32 v93, 1.0, v93
	v_rcp_f32_e32 v93, v93
	s_nop 0
	v_sub_f32_e32 v93, 1.0, v93
	v_mul_f32_e32 v54, v54, v93
	v_bfe_u32 v93, v54, 16, 1
	v_add3_u32 v54, v54, v93, s97
	global_store_short_d16_hi v[84:85], v54, off
	v_lshl_add_u64 v[84:85], v[84:85], 0, s[22:23]
	v_lshlrev_b32_e32 v54, 16, v103
	v_fma_f32 v54, v92, v54, v55
	v_mul_f32_e32 v55, 0x3d372713, v54
	v_mul_f32_e32 v55, v54, v55
	v_fma_f32 v55, v54, v55, v54
	v_mul_f32_e32 v55, 0x3f4c422a, v55
	v_add_f32_e32 v55, v55, v55
	v_mul_f32_e32 v55, 0x3fb8aa3b, v55
	v_exp_f32_e32 v55, v55
	s_nop 0
	v_add_f32_e32 v55, 1.0, v55
	v_rcp_f32_e32 v55, v55
	s_nop 0
	v_sub_f32_e32 v55, 1.0, v55
	v_mul_f32_e32 v54, v54, v55
	v_bfe_u32 v55, v54, 16, 1
	v_add3_u32 v93, v54, v55, s97
	v_lshl_add_u64 v[54:55], s[8:9], 0, v[96:97]
	global_store_short_d16_hi v[54:55], v93, off
	v_or_b32_e32 v54, 0x2000, v94
	v_mov_b32_e32 v55, v95
	v_lshl_add_u64 v[96:97], s[6:7], 0, v[54:55]
	v_lshl_add_u64 v[54:55], s[8:9], 0, v[54:55]
	v_or_b32_e32 v94, 0x3000, v94
	v_lshlrev_b32_e32 v93, 16, v104
	v_fma_f32 v56, v92, v93, v56
	v_mul_f32_e32 v93, 0x3d372713, v56
	v_mul_f32_e32 v93, v56, v93
	v_fma_f32 v93, v56, v93, v56
	v_mul_f32_e32 v93, 0x3f4c422a, v93
	v_add_f32_e32 v93, v93, v93
	v_mul_f32_e32 v93, 0x3fb8aa3b, v93
	v_exp_f32_e32 v93, v93
	s_nop 0
	v_add_f32_e32 v93, 1.0, v93
	v_rcp_f32_e32 v93, v93
	s_nop 0
	v_sub_f32_e32 v93, 1.0, v93
	v_mul_f32_e32 v56, v56, v93
	v_bfe_u32 v93, v56, 16, 1
	v_add3_u32 v56, v56, v93, s97
	global_store_short_d16_hi v[54:55], v56, off
	v_lshl_add_u64 v[54:55], s[6:7], 0, v[94:95]
	v_lshlrev_b32_e32 v54, 16, v105
	v_fmac_f32_e32 v57, v92, v54
	v_mul_f32_e32 v54, 0x3d372713, v57
	v_mul_f32_e32 v54, v57, v54
	v_fma_f32 v54, v57, v54, v57
	v_mul_f32_e32 v54, 0x3f4c422a, v54
	v_add_f32_e32 v54, v54, v54
	v_mul_f32_e32 v54, 0x3fb8aa3b, v54
	v_exp_f32_e32 v54, v54
	s_nop 0
	v_add_f32_e32 v54, 1.0, v54
	v_rcp_f32_e32 v54, v54
	s_nop 0
	v_sub_f32_e32 v54, 1.0, v54
	v_mul_f32_e32 v54, v57, v54
	v_bfe_u32 v55, v54, 16, 1
	v_add3_u32 v56, v54, v55, s97
	v_lshl_add_u64 v[54:55], s[8:9], 0, v[94:95]
	global_store_short_d16_hi v[54:55], v56, off
	v_mov_b32_e32 v54, v50
	v_mov_b32_e32 v55, v51
	v_mov_b32_e32 v56, v52
	v_mov_b32_e32 v57, v53
	s_cbranch_vccnz .LBB0_1066

	.amdhsa_kernel _Z10fwd_kernel4Args
		.amdhsa_group_segment_fixed_size 0
		.amdhsa_private_segment_fixed_size 0
		.amdhsa_kernarg_size 512
		.amdhsa_user_sgpr_count 2
		.amdhsa_user_sgpr_dispatch_ptr 0
		.amdhsa_user_sgpr_queue_ptr 0
		.amdhsa_user_sgpr_kernarg_segment_ptr 1
		.amdhsa_user_sgpr_dispatch_id 0
		.amdhsa_user_sgpr_kernarg_preload_length 0
		.amdhsa_user_sgpr_kernarg_preload_offset 0
		.amdhsa_user_sgpr_private_segment_size 0
		.amdhsa_uses_dynamic_stack 0
		.amdhsa_enable_private_segment 0
		.amdhsa_system_sgpr_workgroup_id_x 1
		.amdhsa_system_sgpr_workgroup_id_y 0
		.amdhsa_system_sgpr_workgroup_id_z 0
		.amdhsa_system_sgpr_workgroup_info 0
		.amdhsa_system_vgpr_workitem_id 2
		.amdhsa_next_free_vgpr 249
		.amdhsa_next_free_sgpr 102
		.amdhsa_accum_offset 252
		.amdhsa_reserve_vcc 1
		.amdhsa_float_round_mode_32 0
		.amdhsa_float_round_mode_16_64 0
		.amdhsa_float_denorm_mode_32 3
		.amdhsa_float_denorm_mode_16_64 3
		.amdhsa_dx10_clamp 1
		.amdhsa_ieee_mode 1
		.amdhsa_fp16_overflow 0
		.amdhsa_tg_split 0
		.amdhsa_exception_fp_ieee_invalid_op 0
		.amdhsa_exception_fp_denorm_src 0
		.amdhsa_exception_fp_ieee_div_zero 0
		.amdhsa_exception_fp_ieee_overflow 0
		.amdhsa_exception_fp_ieee_underflow 0
		.amdhsa_exception_fp_ieee_inexact 0
		.amdhsa_exception_int_div_zero 0
	.end_amdhsa_kernel

amdhsa.kernels:
  - .agpr_count:     0
    .args:
      - .offset:         0
        .size:           256
        .value_kind:     by_value
      - .offset:         256
        .size:           4
        .value_kind:     hidden_block_count_x
      - .offset:         260
        .size:           4
        .value_kind:     hidden_block_count_y
      - .offset:         264
        .size:           4
        .value_kind:     hidden_block_count_z
      - .offset:         268
        .size:           2
        .value_kind:     hidden_group_size_x
      - .offset:         270
        .size:           2
        .value_kind:     hidden_group_size_y
      - .offset:         272
        .size:           2
        .value_kind:     hidden_group_size_z
      - .offset:         274
        .size:           2
        .value_kind:     hidden_remainder_x
      - .offset:         276
        .size:           2
        .value_kind:     hidden_remainder_y
      - .offset:         278
        .size:           2
        .value_kind:     hidden_remainder_z
      - .offset:         296
        .size:           8
        .value_kind:     hidden_global_offset_x
      - .offset:         304
        .size:           8
        .value_kind:     hidden_global_offset_y
      - .offset:         312
        .size:           8
        .value_kind:     hidden_global_offset_z
      - .offset:         320
        .size:           2
        .value_kind:     hidden_grid_dims
      - .offset:         344
        .size:           8
        .value_kind:     hidden_multigrid_sync_arg
      - .offset:         376
        .size:           4
        .value_kind:     hidden_dynamic_lds_size
    .group_segment_fixed_size: 0
    .kernarg_segment_align: 8
    .kernarg_segment_size: 512
    .language:       OpenCL C
    .language_version:
      - 2
      - 0
    .max_flat_workgroup_size: 512
    .name:           _Z10fwd_kernel4Args
    .private_segment_fixed_size: 0
    .sgpr_count:     108
    .sgpr_spill_count: 50
    .symbol:         _Z10fwd_kernel4Args.kd
    .uniform_work_group_size: 1
    .uses_dynamic_stack: false
    .vgpr_count:     249
    .vgpr_spill_count: 0
    .wavefront_size: 64
